# FFN up-projection epilogue (conv+gate): 288 packed f32 VALU ops per wave replaced by scalar f32 pairs (same arithmetic)
# baseline (speedup 1.0000x reference)
.LBB0_1260:
	s_or_b64 exec, exec, s[4:5]
	v_lshl_add_u32 v176, s8, 7, v160
	v_ashrrev_i32_e32 v177, 31, v176
	v_lshlrev_b64 v[128:129], 2, v[176:177]
	v_lshl_add_u64 v[180:181], s[16:17], 0, v[128:129]
	v_add_co_u32_e32 v136, vcc, 0xb000, v180
	s_mov_b32 s4, 0x16000
	s_nop 0
	v_addc_co_u32_e32 v137, vcc, 0, v181, vcc
	v_add_co_u32_e32 v184, vcc, s4, v180
	v_lshl_add_u64 v[178:179], s[20:21], 0, v[128:129]
	s_nop 0
	v_addc_co_u32_e32 v185, vcc, 0, v181, vcc
	s_movk_i32 s4, 0x5000
	v_add_co_u32_e32 v182, vcc, s4, v178
	s_waitcnt lgkmcnt(0)
	s_barrier
	s_nop 0
	v_addc_co_u32_e32 v183, vcc, 0, v179, vcc
	v_add_co_u32_e32 v186, vcc, s4, v180
	s_mov_b32 s4, 0x10000
	s_nop 0
	v_addc_co_u32_e32 v187, vcc, 0, v181, vcc
	v_add_co_u32_e32 v188, vcc, s4, v180
	s_mov_b32 s4, 0x1b000
	s_nop 0
	v_addc_co_u32_e32 v189, vcc, 0, v181, vcc
	global_load_dwordx4 v[128:131], v[178:179], off
	global_load_dwordx4 v[132:135], v[180:181], off
	global_load_dwordx4 v[148:151], v[136:137], off
	global_load_dwordx4 v[152:155], v[184:185], off
	s_nop 0
	global_load_dwordx4 v[136:139], v[182:183], off offset:2048
	global_load_dwordx4 v[140:143], v[186:187], off offset:2048
	global_load_dwordx4 v[144:147], v[188:189], off offset:2048
	v_add_co_u32_e32 v190, vcc, s4, v180
	v_readlane_b32 s4, v254, 40
	s_nop 0
	v_addc_co_u32_e32 v191, vcc, 0, v181, vcc
	global_load_dwordx4 v[156:159], v[190:191], off offset:2048
	v_lshlrev_b32_e32 v204, 2, v160
	v_or_b32_e32 v161, s4, v201
	v_add_u32_e32 v203, s87, v204
	v_readlane_b32 s4, v254, 42
	v_cmp_eq_u32_e64 s[8:9], 0, v161
	ds_read_b128 v[160:163], v203
	v_add_u32_e32 v202, s4, v204
	ds_read_b128 v[172:175], v202
	ds_read_b128 v[164:167], v203 offset:512
	ds_read_b128 v[168:171], v202 offset:512
	s_lshl_b32 s25, s14, 2
	s_mul_hi_i32 s4, s25, 0xb000
	s_waitcnt lgkmcnt(0)
	v_mov_b32_dpp v160, v112 row_shr:1 row_mask:0xf bank_mask:0xf
	v_mov_b32_dpp v161, v113 row_shr:1 row_mask:0xf bank_mask:0xf
	v_mov_b32_dpp v162, v114 row_shr:1 row_mask:0xf bank_mask:0xf
	v_mov_b32_dpp v163, v115 row_shr:1 row_mask:0xf bank_mask:0xf
	v_mov_b32_dpp v164, v96 row_shr:1 row_mask:0xf bank_mask:0xf
	v_mov_b32_dpp v165, v97 row_shr:1 row_mask:0xf bank_mask:0xf
	v_mov_b32_dpp v166, v98 row_shr:1 row_mask:0xf bank_mask:0xf
	v_mov_b32_dpp v167, v99 row_shr:1 row_mask:0xf bank_mask:0xf
	v_mov_b32_dpp v172, v124 row_shl:1 row_mask:0xf bank_mask:0xf
	v_mov_b32_dpp v173, v125 row_shl:1 row_mask:0xf bank_mask:0xf
	v_mov_b32_dpp v174, v126 row_shl:1 row_mask:0xf bank_mask:0xf
	v_mov_b32_dpp v175, v127 row_shl:1 row_mask:0xf bank_mask:0xf
	v_mov_b32_dpp v168, v108 row_shl:1 row_mask:0xf bank_mask:0xf
	v_mov_b32_dpp v169, v109 row_shl:1 row_mask:0xf bank_mask:0xf
	v_mov_b32_dpp v170, v110 row_shl:1 row_mask:0xf bank_mask:0xf
	v_mov_b32_dpp v171, v111 row_shl:1 row_mask:0xf bank_mask:0xf
	s_mul_i32 s5, s25, 0xb000
	s_waitcnt vmcnt(0)
	v_fma_f32 v206, v124, v148, v128
	v_fma_f32 v207, v125, v149, v129
	v_fma_f32 v208, v126, v150, v130
	v_fma_f32 v209, v127, v151, v131
	v_fma_f32 v160, v132, v160, v206
	v_fma_f32 v161, v133, v161, v207
	v_fma_f32 v162, v134, v162, v208
	v_fma_f32 v163, v135, v163, v209
	v_fma_f32 v206, v108, v144, v136
	v_fma_f32 v207, v109, v145, v137
	v_fma_f32 v208, v110, v146, v138
	v_fma_f32 v209, v111, v147, v139
	v_fma_f32 v164, v140, v164, v206
	v_fma_f32 v165, v141, v165, v207
	v_fma_f32 v166, v142, v166, v208
	v_fma_f32 v167, v143, v167, v209
	v_fma_f32 v160, v120, v152, v160
	v_fma_f32 v161, v121, v153, v161
	v_fma_f32 v162, v122, v154, v162
	v_fma_f32 v163, v123, v155, v163
	v_fma_f32 v164, v104, v156, v164
	v_fma_f32 v165, v105, v157, v165
	v_fma_f32 v166, v106, v158, v166
	v_fma_f32 v167, v107, v159, v167
	s_and_saveexec_b64 s[34:35], s[8:9]
	s_mov_b32 s75, 0x20000
	s_cbranch_execz .LBB0_1262
	s_add_u32 s36, s83, s5
	s_addc_u32 s37, s84, s4
	v_lshl_add_u64 v[206:207], v[176:177], 2, s[36:37]
	v_add_co_u32_e32 v208, vcc, 0x5000, v206
	global_store_dwordx4 v[206:207], v[160:163], off
	s_nop 0
	v_addc_co_u32_e32 v209, vcc, 0, v207, vcc
	global_store_dwordx4 v[208:209], v[164:167], off offset:2048
	v_add_co_u32_e32 v208, vcc, 0xb000, v206
	s_nop 1
	v_addc_co_u32_e32 v209, vcc, 0, v207, vcc
	v_add_co_u32_e32 v206, vcc, 0x10000, v206
	global_store_dwordx4 v[208:209], v[124:127], off
	s_nop 0
	v_addc_co_u32_e32 v207, vcc, 0, v207, vcc
	global_store_dwordx4 v[206:207], v[108:111], off offset:2048
.LBB0_1262:
	s_or_b64 exec, exec, s[34:35]
	v_fma_f32 v206, v120, v148, v128
	v_fma_f32 v207, v121, v149, v129
	s_or_b32 s27, s25, 2
	v_fma_f32 v124, v124, v132, v206
	v_fma_f32 v125, v125, v133, v207
	v_fma_f32 v206, v116, v148, v128
	v_fma_f32 v207, v117, v149, v129
	v_fma_f32 v124, v116, v152, v124
	v_fma_f32 v125, v117, v153, v125
	v_fma_f32 v120, v120, v132, v206
	v_fma_f32 v121, v121, v133, v207
	v_readlane_b32 s25, v254, 43
	v_fma_f32 v120, v112, v152, v120
	v_fma_f32 v121, v113, v153, v121
	v_fma_f32 v112, v112, v148, v128
	v_fma_f32 v113, v113, v149, v129
	v_readlane_b32 s34, v254, 23
	v_fma_f32 v112, v116, v132, v112
	v_fma_f32 v113, v117, v133, v113
	v_fma_f32 v116, v122, v150, v130
	v_fma_f32 v117, v123, v151, v131
	v_fma_f32 v112, v152, v172, v112
	v_fma_f32 v113, v153, v173, v113
	v_fma_f32 v116, v126, v134, v116
	v_fma_f32 v117, v127, v135, v117
	v_fma_f32 v126, v118, v150, v130
	v_fma_f32 v127, v119, v151, v131
	v_fma_f32 v116, v118, v154, v116
	v_fma_f32 v117, v119, v155, v117
	v_fma_f32 v122, v122, v134, v126
	v_fma_f32 v123, v123, v135, v127
	v_mul_f32_e32 v126, v162, v166
	v_mul_f32_e32 v127, v163, v167
	v_fma_f32 v122, v114, v154, v122
	v_fma_f32 v123, v115, v155, v123
	v_fma_f32 v114, v114, v150, v130
	v_fma_f32 v115, v115, v151, v131
	v_readlane_b32 s35, v254, 24
	v_fma_f32 v114, v118, v134, v114
	v_fma_f32 v115, v119, v135, v115
	v_fma_f32 v118, v104, v144, v136
	v_fma_f32 v119, v105, v145, v137
	v_fma_f32 v114, v154, v174, v114
	v_fma_f32 v115, v155, v175, v115
	v_fma_f32 v108, v108, v140, v118
	v_fma_f32 v109, v109, v141, v119
	v_fma_f32 v118, v100, v144, v136
	v_fma_f32 v119, v101, v145, v137
	v_fma_f32 v108, v100, v156, v108
	v_fma_f32 v109, v101, v157, v109
	v_fma_f32 v104, v104, v140, v118
	v_fma_f32 v105, v105, v141, v119
	s_and_b64 s[10:11], s[34:35], s[10:11]
	v_fma_f32 v104, v96, v156, v104
	v_fma_f32 v105, v97, v157, v105
	v_fma_f32 v96, v96, v144, v136
	v_fma_f32 v97, v97, v145, v137
	s_nop 0
	v_fma_f32 v96, v100, v140, v96
	v_fma_f32 v97, v101, v141, v97
	v_exp_f32_e32 v100, v166
	v_fma_f32 v118, v156, v168, v96
	v_fma_f32 v119, v157, v169, v97
	v_fma_f32 v96, v106, v146, v138
	v_fma_f32 v97, v107, v147, v139
	v_exp_f32_e32 v101, v167
	v_fma_f32 v96, v110, v142, v96
	v_fma_f32 v97, v111, v143, v97
	v_add_f32_e32 v100, 1.0, v100
	v_add_f32_e32 v101, 1.0, v101
	v_fma_f32 v110, v102, v158, v96
	v_fma_f32 v111, v103, v159, v97
	v_fma_f32 v96, v102, v146, v138
	v_fma_f32 v97, v103, v147, v139
	v_rcp_f32_e32 v100, v100
	v_fma_f32 v96, v106, v142, v96
	v_fma_f32 v97, v107, v143, v97
	v_rcp_f32_e32 v101, v101
	v_fma_f32 v106, v98, v158, v96
	v_fma_f32 v107, v99, v159, v97
	v_exp_f32_e32 v96, v164
	v_exp_f32_e32 v97, v165
	v_fma_f32 v98, v98, v146, v138
	v_fma_f32 v99, v99, v147, v139
	v_mul_f32_e32 v100, v126, v100
	v_mul_f32_e32 v101, v127, v101
	v_fma_f32 v98, v102, v142, v98
	v_fma_f32 v99, v103, v143, v99
	v_add_f32_e32 v96, 1.0, v96
	v_add_f32_e32 v97, 1.0, v97
	v_mul_f32_e32 v102, v160, v164
	v_mul_f32_e32 v103, v161, v165
	v_rcp_f32_e32 v96, v96
	v_rcp_f32_e32 v97, v97
	v_fma_f32 v98, v158, v170, v98
	v_fma_f32 v99, v159, v171, v99
	v_add_u32_e32 v160, s89, v204
	v_add_u32_e32 v161, s25, v204
	v_mul_f32_e32 v96, v102, v96
	v_mul_f32_e32 v97, v103, v97
	v_exp_f32_e32 v102, v108
	v_exp_f32_e32 v103, v109
	v_cvt_pk_bf16_f32 v96, v96, v97
	v_cvt_pk_bf16_f32 v97, v100, v101
	v_mul_f32_e32 v108, v124, v108
	v_mul_f32_e32 v109, v125, v109
	v_add_f32_e32 v100, 1.0, v102
	v_add_f32_e32 v101, 1.0, v103
	v_exp_f32_e32 v102, v110
	v_exp_f32_e32 v103, v111
	v_rcp_f32_e32 v100, v100
	v_rcp_f32_e32 v101, v101
	v_mul_f32_e32 v110, v116, v110
	v_mul_f32_e32 v111, v117, v111
	v_add_f32_e32 v102, 1.0, v102
	v_add_f32_e32 v103, 1.0, v103
	s_mul_hi_i32 s25, s27, 0xb000
	v_rcp_f32_e32 v102, v102
	v_rcp_f32_e32 v103, v103
	v_mul_f32_e32 v100, v108, v100
	v_mul_f32_e32 v101, v109, v101
	v_exp_f32_e32 v108, v104
	v_exp_f32_e32 v109, v105
	v_mul_f32_e32 v102, v110, v102
	v_mul_f32_e32 v103, v111, v103
	v_cvt_pk_bf16_f32 v100, v100, v101
	v_mul_f32_e32 v104, v120, v104
	v_mul_f32_e32 v105, v121, v105
	v_cvt_pk_bf16_f32 v101, v102, v103
	v_add_f32_e32 v102, 1.0, v108
	v_add_f32_e32 v103, 1.0, v109
	v_exp_f32_e32 v108, v106
	v_rcp_f32_e32 v102, v102
	v_rcp_f32_e32 v103, v103
	v_exp_f32_e32 v109, v107
	v_mul_f32_e32 v106, v122, v106
	v_mul_f32_e32 v107, v123, v107
	s_mul_i32 s27, s27, 0xb000
	v_mul_f32_e32 v102, v104, v102
	v_mul_f32_e32 v103, v105, v103
	s_nop 0
	v_cvt_pk_bf16_f32 v104, v102, v103
	v_add_f32_e32 v102, 1.0, v108
	v_add_f32_e32 v103, 1.0, v109
	v_exp_f32_e32 v108, v118
	v_rcp_f32_e32 v102, v102
	v_rcp_f32_e32 v103, v103
	v_exp_f32_e32 v109, v119
	v_mul_f32_e32 v102, v106, v102
	v_mul_f32_e32 v103, v107, v103
	v_exp_f32_e32 v106, v98
	v_exp_f32_e32 v107, v99
	v_cvt_pk_bf16_f32 v105, v102, v103
	v_add_f32_e32 v102, 1.0, v108
	v_add_f32_e32 v103, 1.0, v109
	v_mul_f32_e32 v108, v112, v118
	v_mul_f32_e32 v109, v113, v119
	v_add_f32_e32 v106, 1.0, v106
	v_add_f32_e32 v107, 1.0, v107
	v_rcp_f32_e32 v102, v102
	v_rcp_f32_e32 v103, v103
	v_rcp_f32_e32 v106, v106
	v_rcp_f32_e32 v107, v107
	v_mul_f32_e32 v98, v114, v98
	v_mul_f32_e32 v99, v115, v99
	v_mul_f32_e32 v102, v108, v102
	v_mul_f32_e32 v103, v109, v103
	v_mul_f32_e32 v98, v98, v106
	v_mul_f32_e32 v99, v99, v107
	v_cvt_pk_bf16_f32 v108, v102, v103
	s_nop 0
	v_cvt_pk_bf16_f32 v109, v98, v99
	ds_read_b128 v[118:121], v160
	ds_read_b128 v[110:113], v161
	ds_read_b128 v[122:125], v160 offset:512
	ds_read_b128 v[114:117], v161 offset:512
	v_fma_f32 v98, v80, v148, v128
	v_fma_f32 v99, v81, v149, v129
	s_waitcnt lgkmcnt(2)
	v_mov_b32_dpp v110, v92 row_shl:1 row_mask:0xf bank_mask:0xf
	v_mov_b32_dpp v111, v93 row_shl:1 row_mask:0xf bank_mask:0xf
	v_fma_f32 v98, v84, v132, v98
	v_fma_f32 v99, v85, v133, v99
	v_mov_b32_dpp v112, v94 row_shl:1 row_mask:0xf bank_mask:0xf
	v_fma_f32 v110, v152, v110, v98
	v_fma_f32 v111, v153, v111, v99
	v_fma_f32 v98, v82, v150, v130
	v_fma_f32 v99, v83, v151, v131
	v_mov_b32_dpp v113, v95 row_shl:1 row_mask:0xf bank_mask:0xf
	v_fma_f32 v98, v86, v134, v98
	v_fma_f32 v99, v87, v135, v99
	s_waitcnt lgkmcnt(0)
	v_mov_b32_dpp v114, v76 row_shl:1 row_mask:0xf bank_mask:0xf
	v_fma_f32 v112, v154, v112, v98
	v_fma_f32 v113, v155, v113, v99
	v_fma_f32 v98, v64, v144, v136
	v_fma_f32 v99, v65, v145, v137
	v_mov_b32_dpp v115, v77 row_shl:1 row_mask:0xf bank_mask:0xf
	v_fma_f32 v98, v68, v140, v98
	v_fma_f32 v99, v69, v141, v99
	v_mov_b32_dpp v116, v78 row_shl:1 row_mask:0xf bank_mask:0xf
	v_fma_f32 v114, v156, v114, v98
	v_fma_f32 v115, v157, v115, v99
	v_fma_f32 v98, v66, v146, v138
	v_fma_f32 v99, v67, v147, v139
	v_mov_b32_dpp v117, v79 row_shl:1 row_mask:0xf bank_mask:0xf
	v_fma_f32 v98, v70, v142, v98
	v_fma_f32 v99, v71, v143, v99
	v_mov_b32_dpp v118, v80 row_shr:1 row_mask:0xf bank_mask:0xf
	v_mov_b32_dpp v119, v81 row_shr:1 row_mask:0xf bank_mask:0xf
	v_mov_b32_dpp v120, v82 row_shr:1 row_mask:0xf bank_mask:0xf
	v_mov_b32_dpp v121, v83 row_shr:1 row_mask:0xf bank_mask:0xf
	v_mov_b32_dpp v122, v64 row_shr:1 row_mask:0xf bank_mask:0xf
	v_mov_b32_dpp v123, v65 row_shr:1 row_mask:0xf bank_mask:0xf
	v_mov_b32_dpp v124, v66 row_shr:1 row_mask:0xf bank_mask:0xf
	v_mov_b32_dpp v125, v67 row_shr:1 row_mask:0xf bank_mask:0xf
	v_fma_f32 v116, v158, v116, v98
	v_fma_f32 v117, v159, v117, v99
	s_and_saveexec_b64 s[34:35], s[10:11]
	s_cbranch_execz .LBB0_1264
	s_add_u32 s36, s83, s27
	s_addc_u32 s37, s84, s25
	v_lshl_add_u64 v[98:99], v[176:177], 2, s[36:37]
	v_add_co_u32_e32 v102, vcc, 0x5000, v98
	global_store_dwordx4 v[98:99], v[110:113], off
	s_nop 0
	v_addc_co_u32_e32 v103, vcc, 0, v99, vcc
	global_store_dwordx4 v[102:103], v[114:117], off offset:2048
	v_add_co_u32_e32 v102, vcc, 0xb000, v98
	s_nop 1
	v_addc_co_u32_e32 v103, vcc, 0, v99, vcc
	v_add_co_u32_e32 v98, vcc, 0x10000, v98
	global_store_dwordx4 v[102:103], v[80:83], off
	s_nop 0
	v_addc_co_u32_e32 v99, vcc, 0, v99, vcc
	global_store_dwordx4 v[98:99], v[64:67], off offset:2048
.LBB0_1264:
	s_or_b64 exec, exec, s[34:35]
	v_fma_f32 v102, v88, v148, v128
	v_fma_f32 v103, v89, v149, v129
	v_fma_f32 v98, v92, v148, v128
	v_fma_f32 v99, v93, v149, v129
	v_fma_f32 v92, v92, v132, v102
	v_fma_f32 v93, v93, v133, v103
	v_fma_f32 v98, v132, v118, v98
	v_fma_f32 v99, v133, v119, v99
	v_fma_f32 v92, v84, v152, v92
	v_fma_f32 v93, v85, v153, v93
	v_fma_f32 v84, v84, v148, v128
	v_fma_f32 v85, v85, v149, v129
	v_fma_f32 v98, v88, v152, v98
	v_fma_f32 v99, v89, v153, v99
	v_fma_f32 v84, v88, v132, v84
	v_fma_f32 v85, v89, v133, v85
	v_fma_f32 v88, v90, v150, v130
	v_fma_f32 v89, v91, v151, v131
	v_fma_f32 v80, v80, v152, v84
	v_fma_f32 v81, v81, v153, v85
	v_fma_f32 v84, v94, v150, v130
	v_fma_f32 v85, v95, v151, v131
	v_fma_f32 v88, v94, v134, v88
	v_fma_f32 v89, v95, v135, v89
	v_fma_f32 v84, v134, v120, v84
	v_fma_f32 v85, v135, v121, v85
	v_fma_f32 v88, v86, v154, v88
	v_fma_f32 v89, v87, v155, v89
	v_fma_f32 v86, v86, v150, v130
	v_fma_f32 v87, v87, v151, v131
	v_fma_f32 v84, v90, v154, v84
	v_fma_f32 v85, v91, v155, v85
	v_fma_f32 v86, v90, v134, v86
	v_fma_f32 v87, v91, v135, v87
	v_fma_f32 v90, v72, v144, v136
	v_fma_f32 v91, v73, v145, v137
	v_fma_f32 v82, v82, v154, v86
	v_fma_f32 v83, v83, v155, v87
	v_fma_f32 v86, v76, v144, v136
	v_fma_f32 v87, v77, v145, v137
	v_fma_f32 v76, v76, v140, v90
	v_fma_f32 v77, v77, v141, v91
	v_fma_f32 v86, v140, v122, v86
	v_fma_f32 v87, v141, v123, v87
	v_fma_f32 v76, v68, v156, v76
	v_fma_f32 v77, v69, v157, v77
	v_fma_f32 v68, v68, v144, v136
	v_fma_f32 v69, v69, v145, v137
	v_fma_f32 v86, v72, v156, v86
	v_fma_f32 v87, v73, v157, v87
	v_fma_f32 v68, v72, v140, v68
	v_fma_f32 v69, v73, v141, v69
	s_nop 0
	v_fma_f32 v72, v64, v156, v68
	v_fma_f32 v73, v65, v157, v69
	v_fma_f32 v64, v78, v146, v138
	v_fma_f32 v65, v79, v147, v139
	s_nop 0
	v_fma_f32 v64, v142, v124, v64
	v_fma_f32 v65, v143, v125, v65
	s_nop 0
	v_fma_f32 v68, v74, v158, v64
	v_fma_f32 v69, v75, v159, v65
	v_fma_f32 v64, v74, v146, v138
	v_fma_f32 v65, v75, v147, v139
	s_nop 0
	v_fma_f32 v64, v78, v142, v64
	v_fma_f32 v65, v79, v143, v65
	s_nop 0
	v_fma_f32 v78, v70, v158, v64
	v_fma_f32 v79, v71, v159, v65
	v_exp_f32_e32 v64, v86
	v_exp_f32_e32 v65, v87
	v_fma_f32 v70, v70, v146, v138
	v_fma_f32 v71, v71, v147, v139
	v_add_f32_e32 v64, 1.0, v64
	v_add_f32_e32 v65, 1.0, v65
	v_fma_f32 v70, v74, v142, v70
	v_fma_f32 v71, v75, v143, v71
	v_rcp_f32_e32 v64, v64
	v_fma_f32 v66, v66, v158, v70
	v_fma_f32 v67, v67, v159, v71
	v_exp_f32_e32 v70, v68
	v_exp_f32_e32 v71, v69
	v_rcp_f32_e32 v65, v65
	v_mul_f32_e32 v74, v98, v86
	v_mul_f32_e32 v75, v99, v87
	v_mul_f32_e32 v68, v84, v68
	v_mul_f32_e32 v69, v85, v69
	v_add_f32_e32 v70, 1.0, v70
	v_add_f32_e32 v71, 1.0, v71
	v_mul_f32_e32 v64, v74, v64
	v_mul_f32_e32 v65, v75, v65
	v_rcp_f32_e32 v70, v70
	v_rcp_f32_e32 v71, v71
	v_exp_f32_e32 v74, v76
	v_exp_f32_e32 v75, v77
	v_cvt_pk_bf16_f32 v64, v64, v65
	v_mul_f32_e32 v68, v68, v70
	v_mul_f32_e32 v69, v69, v71
	v_exp_f32_e32 v70, v78
	v_exp_f32_e32 v71, v79
	v_cvt_pk_bf16_f32 v65, v68, v69
	v_add_f32_e32 v68, 1.0, v74
	v_add_f32_e32 v69, 1.0, v75
	v_mul_f32_e32 v74, v92, v76
	v_mul_f32_e32 v75, v93, v77
	v_rcp_f32_e32 v68, v68
	v_rcp_f32_e32 v69, v69
	v_add_f32_e32 v70, 1.0, v70
	v_add_f32_e32 v71, 1.0, v71
	v_mul_f32_e32 v76, v88, v78
	v_mul_f32_e32 v77, v89, v79
	v_rcp_f32_e32 v70, v70
	v_rcp_f32_e32 v71, v71
	v_mul_f32_e32 v68, v74, v68
	v_mul_f32_e32 v69, v75, v69
	v_exp_f32_e32 v74, v72
	v_exp_f32_e32 v75, v73
	v_mul_f32_e32 v70, v76, v70
	v_mul_f32_e32 v71, v77, v71
	v_cvt_pk_bf16_f32 v68, v68, v69
	v_mul_f32_e32 v72, v80, v72
	v_mul_f32_e32 v73, v81, v73
	v_cvt_pk_bf16_f32 v69, v70, v71
	v_add_f32_e32 v70, 1.0, v74
	v_add_f32_e32 v71, 1.0, v75
	v_exp_f32_e32 v74, v66
	v_rcp_f32_e32 v70, v70
	v_rcp_f32_e32 v71, v71
	v_exp_f32_e32 v75, v67
	v_mul_f32_e32 v66, v82, v66
	v_mul_f32_e32 v67, v83, v67
	v_mul_f32_e32 v70, v72, v70
	v_mul_f32_e32 v71, v73, v71
	s_nop 0
	v_cvt_pk_bf16_f32 v72, v70, v71
	v_add_f32_e32 v70, 1.0, v74
	v_add_f32_e32 v71, 1.0, v75
	v_exp_f32_e32 v74, v114
	v_rcp_f32_e32 v70, v70
	v_rcp_f32_e32 v71, v71
	v_exp_f32_e32 v75, v115
	v_mul_f32_e32 v66, v66, v70
	v_mul_f32_e32 v67, v67, v71
	v_exp_f32_e32 v70, v116
	v_exp_f32_e32 v71, v117
	v_cvt_pk_bf16_f32 v73, v66, v67
	v_add_f32_e32 v66, 1.0, v74
	v_add_f32_e32 v67, 1.0, v75
	v_mul_f32_e32 v74, v110, v114
	v_mul_f32_e32 v75, v111, v115
	v_rcp_f32_e32 v66, v66
	v_rcp_f32_e32 v67, v67
	v_add_f32_e32 v70, 1.0, v70
	v_add_f32_e32 v71, 1.0, v71
	v_mul_f32_e32 v66, v74, v66
	v_mul_f32_e32 v67, v75, v67
	v_rcp_f32_e32 v70, v70
	v_rcp_f32_e32 v71, v71
	v_cvt_pk_bf16_f32 v76, v66, v67
	v_mul_f32_e32 v66, v112, v116
	v_mul_f32_e32 v67, v113, v117
	s_nop 0
	v_mul_f32_e32 v66, v66, v70
	v_mul_f32_e32 v67, v67, v71
	s_nop 0
	v_cvt_pk_bf16_f32 v77, v66, v67
	v_add_co_u32_e32 v66, vcc, s55, v180
	s_nop 1
	v_addc_co_u32_e32 v67, vcc, 0, v181, vcc
	global_load_dwordx4 v[78:81], v[66:67], off offset:16
	global_load_dwordx4 v[82:85], v[178:179], off offset:16
	global_load_dwordx4 v[86:89], v[180:181], off offset:16
	global_load_dwordx4 v[90:93], v[184:185], off offset:16
	global_load_dwordx4 v[112:115], v[188:189], off offset:2064
	global_load_dwordx4 v[116:119], v[182:183], off offset:2064
	global_load_dwordx4 v[120:123], v[186:187], off offset:2064
	global_load_dwordx4 v[124:127], v[190:191], off offset:2064
	ds_read_b128 v[128:131], v203 offset:16
	ds_read_b128 v[132:135], v202 offset:16
	ds_read_b128 v[136:139], v203 offset:528
	ds_read_b128 v[140:143], v202 offset:528
	s_waitcnt lgkmcnt(3)
	v_mov_b32_dpp v128, v48 row_shr:1 row_mask:0xf bank_mask:0xf
	v_mov_b32_dpp v129, v49 row_shr:1 row_mask:0xf bank_mask:0xf
	v_mov_b32_dpp v130, v50 row_shr:1 row_mask:0xf bank_mask:0xf
	v_mov_b32_dpp v131, v51 row_shr:1 row_mask:0xf bank_mask:0xf
	s_waitcnt lgkmcnt(1)
	v_mov_b32_dpp v136, v32 row_shr:1 row_mask:0xf bank_mask:0xf
	v_mov_b32_dpp v137, v33 row_shr:1 row_mask:0xf bank_mask:0xf
	v_mov_b32_dpp v138, v34 row_shr:1 row_mask:0xf bank_mask:0xf
	v_mov_b32_dpp v139, v35 row_shr:1 row_mask:0xf bank_mask:0xf
	v_mov_b32_dpp v132, v60 row_shl:1 row_mask:0xf bank_mask:0xf
	v_mov_b32_dpp v133, v61 row_shl:1 row_mask:0xf bank_mask:0xf
	v_mov_b32_dpp v134, v62 row_shl:1 row_mask:0xf bank_mask:0xf
	v_mov_b32_dpp v135, v63 row_shl:1 row_mask:0xf bank_mask:0xf
	s_waitcnt lgkmcnt(0)
	v_mov_b32_dpp v140, v44 row_shl:1 row_mask:0xf bank_mask:0xf
	v_mov_b32_dpp v141, v45 row_shl:1 row_mask:0xf bank_mask:0xf
	v_mov_b32_dpp v142, v46 row_shl:1 row_mask:0xf bank_mask:0xf
	v_mov_b32_dpp v143, v47 row_shl:1 row_mask:0xf bank_mask:0xf
	s_waitcnt vmcnt(6)
	v_fma_f32 v66, v60, v78, v82
	v_fma_f32 v67, v61, v79, v83
	s_waitcnt vmcnt(5)
	v_fma_f32 v66, v86, v128, v66
	v_fma_f32 v67, v87, v129, v67
	s_waitcnt vmcnt(4)
	v_fma_f32 v128, v56, v90, v66
	v_fma_f32 v129, v57, v91, v67
	v_fma_f32 v66, v62, v80, v84
	v_fma_f32 v67, v63, v81, v85
	s_nop 0
	v_fma_f32 v66, v88, v130, v66
	v_fma_f32 v67, v89, v131, v67
	s_nop 0
	v_fma_f32 v130, v58, v92, v66
	v_fma_f32 v131, v59, v93, v67
	s_waitcnt vmcnt(2)
	v_fma_f32 v66, v44, v112, v116
	v_fma_f32 v67, v45, v113, v117
	s_waitcnt vmcnt(1)
	v_fma_f32 v66, v120, v136, v66
	v_fma_f32 v67, v121, v137, v67
	s_waitcnt vmcnt(0)
	v_fma_f32 v136, v40, v124, v66
	v_fma_f32 v137, v41, v125, v67
	v_fma_f32 v66, v46, v114, v118
	v_fma_f32 v67, v47, v115, v119
	s_nop 0
	v_fma_f32 v66, v122, v138, v66
	v_fma_f32 v67, v123, v139, v67
	s_nop 0
	v_fma_f32 v138, v42, v126, v66
	v_fma_f32 v139, v43, v127, v67
	s_and_saveexec_b64 s[34:35], s[8:9]
	s_cbranch_execz .LBB0_1266
	s_add_u32 s8, s83, s5
	s_addc_u32 s9, s84, s4
	v_lshl_add_u64 v[66:67], v[176:177], 2, s[8:9]
	v_add_co_u32_e32 v70, vcc, 0x5000, v66
	global_store_dwordx4 v[66:67], v[128:131], off offset:16
	s_nop 0
	v_addc_co_u32_e32 v71, vcc, 0, v67, vcc
	global_store_dwordx4 v[70:71], v[136:139], off offset:2064
	v_add_co_u32_e32 v70, vcc, 0xb000, v66
	s_nop 1
	v_addc_co_u32_e32 v71, vcc, 0, v67, vcc
	v_add_co_u32_e32 v66, vcc, 0x10000, v66
	global_store_dwordx4 v[70:71], v[60:63], off offset:16
	s_nop 0
	v_addc_co_u32_e32 v67, vcc, 0, v67, vcc
	global_store_dwordx4 v[66:67], v[44:47], off offset:2064
.LBB0_1266:
	s_or_b64 exec, exec, s[34:35]
	v_fma_f32 v66, v56, v78, v82
	v_fma_f32 v67, v57, v79, v83
	s_nop 0
	v_fma_f32 v60, v60, v86, v66
	v_fma_f32 v61, v61, v87, v67
	v_fma_f32 v66, v52, v78, v82
	v_fma_f32 v67, v53, v79, v83
	v_fma_f32 v60, v52, v90, v60
	v_fma_f32 v61, v53, v91, v61
	v_fma_f32 v56, v56, v86, v66
	v_fma_f32 v57, v57, v87, v67
	s_nop 0
	v_fma_f32 v56, v48, v90, v56
	v_fma_f32 v57, v49, v91, v57
	v_fma_f32 v48, v48, v78, v82
	v_fma_f32 v49, v49, v79, v83
	s_nop 0
	v_fma_f32 v48, v52, v86, v48
	v_fma_f32 v49, v53, v87, v49
	v_fma_f32 v52, v58, v80, v84
	v_fma_f32 v53, v59, v81, v85
	v_fma_f32 v48, v90, v132, v48
	v_fma_f32 v49, v91, v133, v49
	v_fma_f32 v52, v62, v88, v52
	v_fma_f32 v53, v63, v89, v53
	v_fma_f32 v62, v54, v80, v84
	v_fma_f32 v63, v55, v81, v85
	v_fma_f32 v52, v54, v92, v52
	v_fma_f32 v53, v55, v93, v53
	v_fma_f32 v58, v58, v88, v62
	v_fma_f32 v59, v59, v89, v63
	s_nop 0
	v_fma_f32 v58, v50, v92, v58
	v_fma_f32 v59, v51, v93, v59
	v_fma_f32 v50, v50, v80, v84
	v_fma_f32 v51, v51, v81, v85
	s_nop 0
	v_fma_f32 v50, v54, v88, v50
	v_fma_f32 v51, v55, v89, v51
	v_fma_f32 v54, v40, v112, v116
	v_fma_f32 v55, v41, v113, v117
	v_fma_f32 v50, v92, v134, v50
	v_fma_f32 v51, v93, v135, v51
	v_fma_f32 v44, v44, v120, v54
	v_fma_f32 v45, v45, v121, v55
	v_fma_f32 v54, v36, v112, v116
	v_fma_f32 v55, v37, v113, v117
	v_fma_f32 v44, v36, v124, v44
	v_fma_f32 v45, v37, v125, v45
	v_fma_f32 v40, v40, v120, v54
	v_fma_f32 v41, v41, v121, v55
	v_mul_f32_e32 v54, v128, v136
	v_mul_f32_e32 v55, v129, v137
	v_fma_f32 v40, v32, v124, v40
	v_fma_f32 v41, v33, v125, v41
	v_fma_f32 v32, v32, v112, v116
	v_fma_f32 v33, v33, v113, v117
	s_nop 0
	v_fma_f32 v32, v36, v120, v32
	v_fma_f32 v33, v37, v121, v33
	v_fma_f32 v36, v42, v114, v118
	v_fma_f32 v37, v43, v115, v119
	v_fma_f32 v32, v124, v140, v32
	v_fma_f32 v33, v125, v141, v33
	v_fma_f32 v36, v46, v122, v36
	v_fma_f32 v37, v47, v123, v37
	v_fma_f32 v46, v38, v114, v118
	v_fma_f32 v47, v39, v115, v119
	v_fma_f32 v36, v38, v126, v36
	v_fma_f32 v37, v39, v127, v37
	v_fma_f32 v42, v42, v122, v46
	v_fma_f32 v43, v43, v123, v47
	v_exp_f32_e32 v46, v136
	v_exp_f32_e32 v47, v137
	v_fma_f32 v42, v34, v126, v42
	v_fma_f32 v43, v35, v127, v43
	v_fma_f32 v34, v34, v114, v118
	v_fma_f32 v35, v35, v115, v119
	s_nop 0
	v_fma_f32 v34, v38, v122, v34
	v_fma_f32 v35, v39, v123, v35
	v_add_f32_e32 v38, 1.0, v46
	v_add_f32_e32 v39, 1.0, v47
	v_exp_f32_e32 v46, v138
	v_rcp_f32_e32 v38, v38
	v_rcp_f32_e32 v39, v39
	v_exp_f32_e32 v47, v139
	v_fma_f32 v34, v126, v142, v34
	v_fma_f32 v35, v127, v143, v35
	v_mul_f32_e32 v38, v54, v38
	v_mul_f32_e32 v39, v55, v39
	s_nop 0
	v_cvt_pk_bf16_f32 v98, v38, v39
	v_add_f32_e32 v38, 1.0, v46
	v_add_f32_e32 v39, 1.0, v47
	v_exp_f32_e32 v46, v44
	v_rcp_f32_e32 v38, v38
	v_rcp_f32_e32 v39, v39
	v_exp_f32_e32 v47, v45
	v_mul_f32_e32 v54, v130, v138
	v_mul_f32_e32 v55, v131, v139
	v_mul_f32_e32 v44, v60, v44
	v_mul_f32_e32 v45, v61, v45
	v_mul_f32_e32 v38, v54, v38
	v_mul_f32_e32 v39, v55, v39
	s_nop 0
	v_cvt_pk_bf16_f32 v99, v38, v39
	v_add_f32_e32 v38, 1.0, v46
	v_add_f32_e32 v39, 1.0, v47
	v_exp_f32_e32 v46, v36
	v_rcp_f32_e32 v38, v38
	v_rcp_f32_e32 v39, v39
	v_exp_f32_e32 v47, v37
	v_mul_f32_e32 v36, v52, v36
	v_mul_f32_e32 v37, v53, v37
	v_mul_f32_e32 v38, v44, v38
	v_mul_f32_e32 v39, v45, v39
	s_nop 0
	v_cvt_pk_bf16_f32 v102, v38, v39
	v_add_f32_e32 v38, 1.0, v46
	v_add_f32_e32 v39, 1.0, v47
	v_exp_f32_e32 v44, v40
	v_rcp_f32_e32 v38, v38
	v_rcp_f32_e32 v39, v39
	v_exp_f32_e32 v45, v41
	v_mul_f32_e32 v40, v56, v40
	v_mul_f32_e32 v41, v57, v41
	v_mul_f32_e32 v36, v36, v38
	v_mul_f32_e32 v37, v37, v39
	s_nop 0
	v_cvt_pk_bf16_f32 v103, v36, v37
	v_add_f32_e32 v36, 1.0, v44
	v_add_f32_e32 v37, 1.0, v45
	v_exp_f32_e32 v38, v42
	v_rcp_f32_e32 v36, v36
	v_rcp_f32_e32 v37, v37
	v_exp_f32_e32 v39, v43
	v_mul_f32_e32 v36, v40, v36
	v_mul_f32_e32 v37, v41, v37
	s_nop 0
	v_cvt_pk_bf16_f32 v106, v36, v37
	v_add_f32_e32 v36, 1.0, v38
	v_add_f32_e32 v37, 1.0, v39
	v_exp_f32_e32 v38, v32
	v_rcp_f32_e32 v36, v36
	v_rcp_f32_e32 v37, v37
	v_exp_f32_e32 v39, v33
	v_mul_f32_e32 v40, v58, v42
	v_mul_f32_e32 v41, v59, v43
	v_mul_f32_e32 v32, v48, v32
	v_mul_f32_e32 v33, v49, v33
	v_mul_f32_e32 v36, v40, v36
	v_mul_f32_e32 v37, v41, v37
	v_fma_f32 v48, v8, v78, v82
	v_fma_f32 v49, v9, v79, v83
	v_cvt_pk_bf16_f32 v107, v36, v37
	v_add_f32_e32 v36, 1.0, v38
	v_add_f32_e32 v37, 1.0, v39
	v_exp_f32_e32 v38, v34
	v_exp_f32_e32 v39, v35
	v_rcp_f32_e32 v36, v36
	v_rcp_f32_e32 v37, v37
	v_fma_f32 v48, v20, v86, v48
	v_fma_f32 v49, v21, v87, v49
	v_add_f32_e32 v38, 1.0, v38
	v_add_f32_e32 v39, 1.0, v39
	v_mul_f32_e32 v32, v32, v36
	v_mul_f32_e32 v33, v33, v37
	v_rcp_f32_e32 v38, v38
	v_rcp_f32_e32 v39, v39
	v_cvt_pk_bf16_f32 v110, v32, v33
	v_mul_f32_e32 v32, v50, v34
	v_mul_f32_e32 v33, v51, v35
	s_nop 0
	v_mul_f32_e32 v32, v32, v38
	v_mul_f32_e32 v33, v33, v39
	s_nop 0
	v_cvt_pk_bf16_f32 v111, v32, v33
	ds_read_b128 v[40:43], v160 offset:16
	ds_read_b128 v[32:35], v161 offset:16
	ds_read_b128 v[44:47], v160 offset:528
	ds_read_b128 v[36:39], v161 offset:528
	s_waitcnt lgkmcnt(3)
	v_mov_b32_dpp v40, v8 row_shr:1 row_mask:0xf bank_mask:0xf
	s_waitcnt lgkmcnt(2)
	v_mov_b32_dpp v32, v28 row_shl:1 row_mask:0xf bank_mask:0xf
	v_mov_b32_dpp v33, v29 row_shl:1 row_mask:0xf bank_mask:0xf
	v_fma_f32 v32, v90, v32, v48
	v_fma_f32 v33, v91, v33, v49
	v_fma_f32 v48, v10, v80, v84
	v_fma_f32 v49, v11, v81, v85
	v_mov_b32_dpp v34, v30 row_shl:1 row_mask:0xf bank_mask:0xf
	v_mov_b32_dpp v35, v31 row_shl:1 row_mask:0xf bank_mask:0xf
	v_fma_f32 v48, v22, v88, v48
	v_fma_f32 v49, v23, v89, v49
	s_waitcnt lgkmcnt(0)
	v_mov_b32_dpp v36, v24 row_shl:1 row_mask:0xf bank_mask:0xf
	v_fma_f32 v34, v92, v34, v48
	v_fma_f32 v35, v93, v35, v49
	v_fma_f32 v48, v0, v112, v116
	v_fma_f32 v49, v1, v113, v117
	v_mov_b32_dpp v37, v25 row_shl:1 row_mask:0xf bank_mask:0xf
	v_fma_f32 v48, v4, v120, v48
	v_fma_f32 v49, v5, v121, v49
	v_mov_b32_dpp v38, v26 row_shl:1 row_mask:0xf bank_mask:0xf
	v_fma_f32 v36, v124, v36, v48
	v_fma_f32 v37, v125, v37, v49
	v_fma_f32 v48, v2, v114, v118
	v_fma_f32 v49, v3, v115, v119
	v_mov_b32_dpp v39, v27 row_shl:1 row_mask:0xf bank_mask:0xf
	v_fma_f32 v48, v6, v122, v48
	v_fma_f32 v49, v7, v123, v49
	v_mov_b32_dpp v41, v9 row_shr:1 row_mask:0xf bank_mask:0xf
	v_mov_b32_dpp v42, v10 row_shr:1 row_mask:0xf bank_mask:0xf
	v_mov_b32_dpp v43, v11 row_shr:1 row_mask:0xf bank_mask:0xf
	v_mov_b32_dpp v44, v0 row_shr:1 row_mask:0xf bank_mask:0xf
	v_mov_b32_dpp v45, v1 row_shr:1 row_mask:0xf bank_mask:0xf
	v_mov_b32_dpp v46, v2 row_shr:1 row_mask:0xf bank_mask:0xf
	v_mov_b32_dpp v47, v3 row_shr:1 row_mask:0xf bank_mask:0xf
	v_fma_f32 v38, v126, v38, v48
	v_fma_f32 v39, v127, v39, v49
	s_and_saveexec_b64 s[8:9], s[10:11]
	s_cbranch_execz .LBB0_1268
	s_add_u32 s4, s83, s27
	s_addc_u32 s5, s84, s25
	v_lshl_add_u64 v[48:49], v[176:177], 2, s[4:5]
	v_add_co_u32_e32 v50, vcc, 0x5000, v48
	global_store_dwordx4 v[48:49], v[32:35], off offset:16
	s_nop 0
	v_addc_co_u32_e32 v51, vcc, 0, v49, vcc
	global_store_dwordx4 v[50:51], v[36:39], off offset:2064
	v_add_co_u32_e32 v50, vcc, 0xb000, v48
	s_nop 1
	v_addc_co_u32_e32 v51, vcc, 0, v49, vcc
	v_add_co_u32_e32 v48, vcc, 0x10000, v48
	global_store_dwordx4 v[50:51], v[8:11], off offset:16
	s_nop 0
	v_addc_co_u32_e32 v49, vcc, 0, v49, vcc
	global_store_dwordx4 v[48:49], v[0:3], off offset:2064
.LBB0_1268:
	s_or_b64 exec, exec, s[8:9]
	v_fma_f32 v48, v6, v114, v118
	v_fma_f32 v49, v7, v115, v119
	s_movk_i32 s8, 0x1600
	v_fma_f32 v48, v14, v122, v48
	v_fma_f32 v49, v15, v123, v49
	s_mul_i32 s4, s14, 0x2c0000
	v_fma_f32 v2, v2, v126, v48
	v_fma_f32 v3, v3, v127, v49
	v_fma_f32 v48, v14, v114, v118
	v_fma_f32 v49, v15, v115, v119
	s_mul_hi_i32 s5, s14, 0x2c0000
	v_fma_f32 v48, v26, v122, v48
	v_fma_f32 v49, v27, v123, v49
	v_fma_f32 v26, v26, v114, v118
	v_fma_f32 v27, v27, v115, v119
	v_fma_f32 v6, v6, v126, v48
	v_fma_f32 v7, v7, v127, v49
	v_fma_f32 v26, v122, v46, v26
	v_fma_f32 v27, v123, v47, v27
	s_add_u32 s4, s81, s4
	v_fma_f32 v14, v14, v126, v26
	v_fma_f32 v15, v15, v127, v27
	v_fma_f32 v26, v4, v112, v116
	v_fma_f32 v27, v5, v113, v117
	s_addc_u32 s5, s82, s5
	v_fma_f32 v26, v12, v120, v26
	v_fma_f32 v27, v13, v121, v27
	s_andn2_b64 vcc, exec, s[22:23]
	v_fma_f32 v0, v0, v124, v26
	v_fma_f32 v1, v1, v125, v27
	v_fma_f32 v26, v12, v112, v116
	v_fma_f32 v27, v13, v113, v117
	s_nop 0
	v_fma_f32 v26, v24, v120, v26
	v_fma_f32 v27, v25, v121, v27
	v_fma_f32 v24, v24, v112, v116
	v_fma_f32 v25, v25, v113, v117
	v_fma_f32 v4, v4, v124, v26
	v_fma_f32 v5, v5, v125, v27
	v_fma_f32 v24, v120, v44, v24
	v_fma_f32 v25, v121, v45, v25
	v_fma_f32 v26, v28, v78, v82
	v_fma_f32 v27, v29, v79, v83
	v_fma_f32 v12, v12, v124, v24
	v_fma_f32 v13, v13, v125, v25
	v_fma_f32 v24, v22, v80, v84
	v_fma_f32 v25, v23, v81, v85
	v_fma_f32 v26, v86, v40, v26
	v_fma_f32 v27, v87, v41, v27
	v_fma_f32 v24, v18, v88, v24
	v_fma_f32 v25, v19, v89, v25
	s_nop 0
	v_fma_f32 v10, v10, v92, v24
	v_fma_f32 v11, v11, v93, v25
	v_fma_f32 v24, v18, v80, v84
	v_fma_f32 v25, v19, v81, v85
	s_nop 0
	v_fma_f32 v24, v30, v88, v24
	v_fma_f32 v25, v31, v89, v25
	s_nop 0
	v_fma_f32 v22, v22, v92, v24
	v_fma_f32 v23, v23, v93, v25
	v_fma_f32 v24, v30, v80, v84
	v_fma_f32 v25, v31, v81, v85
	s_nop 0
	v_fma_f32 v24, v88, v42, v24
	v_fma_f32 v25, v89, v43, v25
	s_nop 0
	v_fma_f32 v18, v18, v92, v24
	v_fma_f32 v19, v19, v93, v25
	v_fma_f32 v24, v20, v78, v82
	v_fma_f32 v25, v21, v79, v83
	s_nop 0
	v_fma_f32 v24, v16, v86, v24
	v_fma_f32 v25, v17, v87, v25
	s_nop 0
	v_fma_f32 v8, v8, v90, v24
	v_fma_f32 v9, v9, v91, v25
	v_fma_f32 v24, v16, v78, v82
	v_fma_f32 v25, v17, v79, v83
	v_fma_f32 v16, v16, v90, v26
	v_fma_f32 v17, v17, v91, v27
	v_fma_f32 v24, v28, v86, v24
	v_fma_f32 v25, v29, v87, v25
	v_exp_f32_e32 v26, v14
	v_fma_f32 v20, v20, v90, v24
	v_fma_f32 v21, v21, v91, v25
	v_exp_f32_e32 v24, v12
	v_exp_f32_e32 v25, v13
	v_exp_f32_e32 v27, v15
	v_mul_f32_e32 v12, v16, v12
	v_mul_f32_e32 v13, v17, v13
	v_exp_f32_e32 v16, v4
	v_add_f32_e32 v24, 1.0, v24
	v_add_f32_e32 v25, 1.0, v25
	v_exp_f32_e32 v17, v5
	v_rcp_f32_e32 v24, v24
	v_rcp_f32_e32 v25, v25
	v_mul_f32_e32 v14, v18, v14
	v_mul_f32_e32 v15, v19, v15
	v_mul_f32_e32 v4, v20, v4
	v_mul_f32_e32 v5, v21, v5
	v_mul_f32_e32 v12, v12, v24
	v_mul_f32_e32 v13, v13, v25
	s_nop 0
	v_cvt_pk_bf16_f32 v66, v12, v13
	v_add_f32_e32 v12, 1.0, v26
	v_add_f32_e32 v13, 1.0, v27
	s_nop 0
	v_rcp_f32_e32 v12, v12
	v_rcp_f32_e32 v13, v13
	s_nop 0
	v_mul_f32_e32 v12, v14, v12
	v_mul_f32_e32 v13, v15, v13
	s_nop 0
	v_cvt_pk_bf16_f32 v67, v12, v13
	v_add_f32_e32 v12, 1.0, v16
	v_add_f32_e32 v13, 1.0, v17
	v_exp_f32_e32 v14, v6
	v_rcp_f32_e32 v12, v12
	v_rcp_f32_e32 v13, v13
	v_exp_f32_e32 v15, v7
	v_mul_f32_e32 v6, v22, v6
	v_mul_f32_e32 v7, v23, v7
	v_mul_f32_e32 v4, v4, v12
	v_mul_f32_e32 v5, v5, v13
	s_nop 0
	v_cvt_pk_bf16_f32 v70, v4, v5
	v_add_f32_e32 v4, 1.0, v14
	v_add_f32_e32 v5, 1.0, v15
	v_exp_f32_e32 v12, v0
	v_rcp_f32_e32 v4, v4
	v_rcp_f32_e32 v5, v5
	v_exp_f32_e32 v13, v1
	v_mul_f32_e32 v0, v8, v0
	v_mul_f32_e32 v1, v9, v1
	v_mul_f32_e32 v4, v6, v4
	v_mul_f32_e32 v5, v7, v5
	s_nop 0
	v_cvt_pk_bf16_f32 v71, v4, v5
	v_add_f32_e32 v4, 1.0, v12
	v_add_f32_e32 v5, 1.0, v13
	v_exp_f32_e32 v6, v2
	v_rcp_f32_e32 v4, v4
	v_rcp_f32_e32 v5, v5
	v_exp_f32_e32 v7, v3
	v_mul_f32_e32 v2, v10, v2
	v_mul_f32_e32 v3, v11, v3
	v_mul_f32_e32 v0, v0, v4
	v_mul_f32_e32 v1, v1, v5
	s_nop 0
	v_cvt_pk_bf16_f32 v74, v0, v1
	v_add_f32_e32 v0, 1.0, v6
	v_add_f32_e32 v1, 1.0, v7
	v_exp_f32_e32 v4, v36
	v_rcp_f32_e32 v0, v0
	v_rcp_f32_e32 v1, v1
	v_exp_f32_e32 v5, v37
	v_mul_f32_e32 v0, v2, v0
	v_mul_f32_e32 v1, v3, v1
	v_exp_f32_e32 v2, v38
	v_exp_f32_e32 v3, v39
	v_cvt_pk_bf16_f32 v75, v0, v1
	v_add_f32_e32 v0, 1.0, v4
	v_add_f32_e32 v1, 1.0, v5
	v_mul_f32_e32 v4, v32, v36
	v_mul_f32_e32 v5, v33, v37
	v_rcp_f32_e32 v0, v0
	v_rcp_f32_e32 v1, v1
	v_add_f32_e32 v2, 1.0, v2
	v_add_f32_e32 v3, 1.0, v3
	v_mul_f32_e32 v0, v4, v0
	v_mul_f32_e32 v1, v5, v1
	v_rcp_f32_e32 v2, v2
	v_rcp_f32_e32 v3, v3
	v_cvt_pk_bf16_f32 v78, v0, v1
	v_mul_f32_e32 v0, v34, v38
	v_mul_f32_e32 v1, v35, v39
	s_nop 0
	v_mul_f32_e32 v0, v0, v2
	v_mul_f32_e32 v1, v1, v3
	s_nop 0
	v_cvt_pk_bf16_f32 v79, v0, v1
	v_lshl_or_b32 v0, v201, 2, s64
	v_mul_lo_u32 v0, v0, s8
	v_add_lshl_u32 v0, v0, v176, 1
	v_add_u32_e32 v1, 0x2c00, v0
	global_store_dwordx4 v1, v[100:103], s[4:5]
	v_add_u32_e32 v1, 0x5800, v0
	global_store_dwordx4 v1, v[104:107], s[4:5]
	v_add_u32_e32 v1, 0x8400, v0
	global_store_dwordx4 v1, v[108:111], s[4:5]
	v_add_u32_e32 v1, 0x160000, v0
	global_store_dwordx4 v1, v[64:67], s[4:5]
	v_add_u32_e32 v1, 0x162c00, v0
	global_store_dwordx4 v0, v[96:99], s[4:5]
	global_store_dwordx4 v1, v[68:71], s[4:5]
	v_add_u32_e32 v1, 0x165800, v0
	v_add_u32_e32 v0, 0x168400, v0
	global_store_dwordx4 v1, v[72:75], s[4:5]
	global_store_dwordx4 v0, v[76:79], s[4:5]
	s_mov_b64 s[4:5], -1
	s_cbranch_vccnz .LBB0_1245
	s_and_b64 vcc, exec, s[6:7]
	s_cbranch_vccnz .LBB0_1244
	s_barrier
	s_branch .LBB0_1244
